# accumulator zeroing with 64 v_mov_b64 instead of 128 v_mov_b32
# speedup vs baseline: 1.0139x; 1.0044x over previous
;     __device__ __forceinline__ void operator()(const f32x4 (&acc)[2][2][4][2], const Unit& u, int wr, int wc, int fr, int fq) const {
;         const float* cb = (u.pm >= 64) ? cb_ctx : cb_lat;
;         const int row0 = u.pm * BM + wr * 64 + fr, bcol0 = u.pn * BM + wc * 32 + 8 * fq, ocol = u.pn * HALF + wc * 32 + 8 * fq;
;         constexpr float NL2E = -1.44269504f;
;         f32x2 b0[4], b1[4], bz[4];
; #pragma unroll
;         for (int n = 0; n < 2; ++n) { const f32x4 x0 = *(const f32x4*)(cb + bcol0 + 4 * n), x1 = *(const f32x4*)(cb + bcol0 + HALF + 4 * n);
;             b0[2 * n] = (f32x2){x0[0], x0[1]}; b0[2 * n + 1] = (f32x2){x0[2], x0[3]}; b1[2 * n] = (f32x2){x1[0], x1[1]}; b1[2 * n + 1] = (f32x2){x1[2], x1[3]}; }
; #pragma unroll
;         for (int p = 0; p < 4; ++p) bz[p] = (MODE == 0 ? b0[p] : b1[p]) * NL2E;
;         float sq[2][4];
; #pragma unroll
;         for (int ai = 0; ai < 2; ++ai)
; #pragma unroll
;             for (int m = 0; m < 4; ++m) sq[ai][m] = ssq[row0 + ai * HALF + m * 16];
; template <class Epi, class Sched, bool ALIGN_EPI = false, bool SP2 = false>
; __device__ __forceinline__ void gemm_phase(PG8_LAS unsigned char* lds, const Gemm g, const Sched& S, const Epi& E) {
;     ...
; #pragma unroll
;         for (int a = 0; a < 2; ++a)
; #pragma unroll
;             for (int b = 0; b < 2; ++b)
; #pragma unroll
;                 for (int m = 0; m < 4; ++m)
; #pragma unroll
;                     for (int n = 0; n < 2; ++n) acc[a][b][m][n] = (f32x4){0.f, 0.f, 0.f, 0.f};
;         cur = nxt; cA = nA; cB = nB; ++ui;
.LBB0_440:
	s_add_u32 s42, s60, 0x80
	s_addc_u32 s43, s61, 0
	s_add_u32 s17, s44, 0x100
	s_addc_u32 s60, s45, 0
	s_mov_b32 s44, 0
	s_cmp_gt_i32 s0, 2
	s_cbranch_scc1 .Lpf_skip
	s_lshr_b32 s100, s93, 10
	s_mul_i32 s100, s100, 0x900
	s_add_i32 s100, s100, 0x22000
	v_and_b32_e32 v231, 64, v1
	v_add_lshl_u32 v231, v231, v227, 2
	s_lshl_b32 s101, s14, 10
	s_add_u32 s64, s72, s101
	s_addc_u32 s65, s73, 0
	s_mov_b32 m0, s100
	s_nop 0
	global_load_lds_dword v231, s[64:65]
	s_add_i32 m0, s100, 0xffffff00
	s_nop 0
	global_load_lds_dword v231, s[64:65] offset:512
	s_cmp_gt_i32 s14, 63
	s_cselect_b32 s66, s56, s76
	s_cselect_b32 s67, s57, s77
	s_lshl_b32 s101, s15, 10
	s_add_u32 s66, s66, s101
	s_addc_u32 s67, s67, 0
	v_and_b32_e32 v240, 32, v227
	v_mul_u32_u24_e32 v240, 3, v240
	v_add_u32_e32 v240, v240, v227
	v_and_b32_e32 v241, 0x60, v229
	v_add_lshl_u32 v240, v240, v241, 2
	s_add_i32 m0, s100, 0x200
	s_nop 0
	global_load_lds_dword v240, s[66:67]
.Lpf_skip:
	v_mov_b64_e32 v[2:3], 0
	v_mov_b64_e32 v[4:5], 0
	v_mov_b64_e32 v[6:7], 0
	v_mov_b64_e32 v[8:9], 0
	v_mov_b64_e32 v[10:11], 0
	v_mov_b64_e32 v[12:13], 0
	v_mov_b64_e32 v[14:15], 0
	v_mov_b64_e32 v[16:17], 0
	v_mov_b64_e32 v[18:19], 0
	v_mov_b64_e32 v[20:21], 0
	v_mov_b64_e32 v[22:23], 0
	v_mov_b64_e32 v[24:25], 0
	v_mov_b64_e32 v[26:27], 0
	v_mov_b64_e32 v[28:29], 0
	v_mov_b64_e32 v[30:31], 0
	v_mov_b64_e32 v[32:33], 0
	v_mov_b64_e32 v[34:35], 0
	v_mov_b64_e32 v[36:37], 0
	v_mov_b64_e32 v[38:39], 0
	v_mov_b64_e32 v[40:41], 0
	v_mov_b64_e32 v[42:43], 0
	v_mov_b64_e32 v[44:45], 0
	v_mov_b64_e32 v[46:47], 0
	v_mov_b64_e32 v[48:49], 0
	v_mov_b64_e32 v[50:51], 0
	v_mov_b64_e32 v[52:53], 0
	v_mov_b64_e32 v[54:55], 0
	v_mov_b64_e32 v[56:57], 0
	v_mov_b64_e32 v[58:59], 0
	v_mov_b64_e32 v[60:61], 0
	v_mov_b64_e32 v[62:63], 0
	v_mov_b64_e32 v[64:65], 0
	v_mov_b64_e32 v[66:67], 0
	v_mov_b64_e32 v[68:69], 0
	v_mov_b64_e32 v[70:71], 0
	v_mov_b64_e32 v[72:73], 0
	v_mov_b64_e32 v[74:75], 0
	v_mov_b64_e32 v[76:77], 0
	v_mov_b64_e32 v[78:79], 0
	v_mov_b64_e32 v[80:81], 0
	v_mov_b64_e32 v[82:83], 0
	v_mov_b64_e32 v[84:85], 0
	v_mov_b64_e32 v[86:87], 0
	v_mov_b64_e32 v[88:89], 0
	v_mov_b64_e32 v[90:91], 0
	v_mov_b64_e32 v[92:93], 0
	v_mov_b64_e32 v[94:95], 0
	v_mov_b64_e32 v[96:97], 0
	v_mov_b64_e32 v[98:99], 0
	v_mov_b64_e32 v[100:101], 0
	v_mov_b64_e32 v[102:103], 0
	v_mov_b64_e32 v[104:105], 0
	v_mov_b64_e32 v[106:107], 0
	v_mov_b64_e32 v[108:109], 0
	v_mov_b64_e32 v[110:111], 0
	v_mov_b64_e32 v[112:113], 0
	v_mov_b64_e32 v[114:115], 0
	v_mov_b64_e32 v[116:117], 0
	v_mov_b64_e32 v[118:119], 0
	v_mov_b64_e32 v[120:121], 0
	v_mov_b64_e32 v[122:123], 0
	v_mov_b64_e32 v[124:125], 0
	v_mov_b64_e32 v[126:127], 0
	v_mov_b64_e32 v[128:129], 0
